# K-loops: m0 save/restore around each LDS-DMA issue removed (m0 has no other user), on top of the DMA-first load segments
# baseline (speedup 1.0000x reference)
.LBB0_318:
	v_add_u32_e32 v128, 0x10000, v251
	ds_read_b128 v[146:149], v128
	ds_read_b128 v[150:153], v128 offset:1024
	ds_read_b128 v[154:157], v128 offset:2048
	ds_read_b128 v[158:161], v128 offset:3072
	v_add_u32_e32 v128, 0x14000, v251
	ds_read_b128 v[130:133], v128
	ds_read_b128 v[134:137], v128 offset:1024
	ds_read_b128 v[138:141], v128 offset:2048
	ds_read_b128 v[142:145], v128 offset:3072
	s_add_u32 s42, s93, s9
	s_addc_u32 s43, s94, 0
	s_add_u32 s42, s42, 0xffffff80
	s_addc_u32 s43, s43, -1
	s_mov_b32 m0, s65
	s_nop 0
	global_load_lds_dwordx4 v245, s[42:43]
	s_nop 0
	s_mov_b32 m0, s66
	s_nop 0
	global_load_lds_dwordx4 v247, s[42:43]
	s_cmp_eq_u32 s57, s3
	s_cselect_b32 s73, s55, s94
	s_cselect_b32 s72, s54, s93
	s_cselect_b32 s77, s63, s92
	s_cselect_b32 s76, s62, s8
	s_waitcnt lgkmcnt(0)
	ds_read_b128 v[162:165], v252
	ds_read_b128 v[166:169], v252 offset:1024
	ds_read_b128 v[170:173], v252 offset:2048
	ds_read_b128 v[174:177], v252 offset:3072
	ds_read_b128 v[178:181], v252 offset:4096
	ds_read_b128 v[182:185], v252 offset:5120
	ds_read_b128 v[186:189], v252 offset:6144
	ds_read_b128 v[190:193], v252 offset:7168
	s_waitcnt vmcnt(8)
	s_waitcnt lgkmcnt(0)
	s_barrier
	s_setprio 1
	s_waitcnt lgkmcnt(0)
	v_mfma_f32_16x16x32_bf16 v[124:127], v[146:149], v[162:165], v[124:127]
	v_mfma_f32_16x16x32_bf16 v[120:123], v[154:157], v[162:165], v[120:123]
	v_mfma_f32_16x16x32_bf16 v[108:111], v[146:149], v[170:173], v[108:111]
	v_mfma_f32_16x16x32_bf16 v[104:107], v[154:157], v[170:173], v[104:107]
	v_mfma_f32_16x16x32_bf16 v[92:95], v[146:149], v[178:181], v[92:95]
	v_mfma_f32_16x16x32_bf16 v[88:91], v[154:157], v[178:181], v[88:91]
	v_mfma_f32_16x16x32_bf16 v[76:79], v[146:149], v[186:189], v[76:79]
	v_mfma_f32_16x16x32_bf16 v[72:75], v[154:157], v[186:189], v[72:75]
	v_mfma_f32_16x16x32_bf16 v[124:127], v[150:153], v[166:169], v[124:127]
	v_mfma_f32_16x16x32_bf16 v[120:123], v[158:161], v[166:169], v[120:123]
	v_mfma_f32_16x16x32_bf16 v[108:111], v[150:153], v[174:177], v[108:111]
	v_mfma_f32_16x16x32_bf16 v[104:107], v[158:161], v[174:177], v[104:107]
	v_mfma_f32_16x16x32_bf16 v[92:95], v[150:153], v[182:185], v[92:95]
	v_mfma_f32_16x16x32_bf16 v[88:91], v[158:161], v[182:185], v[88:91]
	v_mfma_f32_16x16x32_bf16 v[76:79], v[150:153], v[190:193], v[76:79]
	v_mfma_f32_16x16x32_bf16 v[72:75], v[158:161], v[190:193], v[72:75]
	s_setprio 0
	s_setprio 1
	v_mfma_f32_16x16x32_bf16 v[116:119], v[130:133], v[162:165], v[116:119]
	v_mfma_f32_16x16x32_bf16 v[112:115], v[138:141], v[162:165], v[112:115]
	v_mfma_f32_16x16x32_bf16 v[100:103], v[130:133], v[170:173], v[100:103]
	v_mfma_f32_16x16x32_bf16 v[96:99], v[138:141], v[170:173], v[96:99]
	v_mfma_f32_16x16x32_bf16 v[84:87], v[130:133], v[178:181], v[84:87]
	v_mfma_f32_16x16x32_bf16 v[80:83], v[138:141], v[178:181], v[80:83]
	v_mfma_f32_16x16x32_bf16 v[68:71], v[130:133], v[186:189], v[68:71]
	v_mfma_f32_16x16x32_bf16 v[64:67], v[138:141], v[186:189], v[64:67]
	v_mfma_f32_16x16x32_bf16 v[116:119], v[134:137], v[166:169], v[116:119]
	v_mfma_f32_16x16x32_bf16 v[112:115], v[142:145], v[166:169], v[112:115]
	v_mfma_f32_16x16x32_bf16 v[100:103], v[134:137], v[174:177], v[100:103]
	v_mfma_f32_16x16x32_bf16 v[96:99], v[142:145], v[174:177], v[96:99]
	v_mfma_f32_16x16x32_bf16 v[84:87], v[134:137], v[182:185], v[84:87]
	v_mfma_f32_16x16x32_bf16 v[80:83], v[142:145], v[182:185], v[80:83]
	v_mfma_f32_16x16x32_bf16 v[68:71], v[134:137], v[190:193], v[68:71]
	v_mfma_f32_16x16x32_bf16 v[64:67], v[142:145], v[190:193], v[64:67]
	s_setprio 0
	s_barrier
	s_mov_b32 m0, s14
	s_nop 0
	global_load_lds_dwordx4 v246, s[76:77]
	s_add_u32 s74, s76, s9
	s_mov_b32 m0, s15
	s_nop 0
	global_load_lds_dwordx4 v248, s[76:77]
	s_addc_u32 s75, s77, 0
	s_mov_b32 m0, s16
	s_nop 0
	global_load_lds_dwordx4 v246, s[74:75]
	v_cndmask_b32_e64 v128, 0, 1, s[68:69]
	s_mov_b32 m0, s17
	s_nop 0
	global_load_lds_dwordx4 v248, s[74:75]
	s_andn2_b64 vcc, exec, s[68:69]
	s_mov_b32 m0, s11
	s_nop 0
	global_load_lds_dwordx4 v245, s[72:73]
	s_nop 0
	s_mov_b32 m0, s19
	s_nop 0
	global_load_lds_dwordx4 v247, s[72:73]
	ds_read_b128 v[186:189], v252 offset:16384
	ds_read_b128 v[190:193], v252 offset:17408
	ds_read_b128 v[178:181], v252 offset:18432
	ds_read_b128 v[182:185], v252 offset:19456
	ds_read_b128 v[170:173], v252 offset:20480
	ds_read_b128 v[174:177], v252 offset:21504
	ds_read_b128 v[162:165], v252 offset:22528
	ds_read_b128 v[166:169], v252 offset:23552
	s_waitcnt vmcnt(8)
	s_waitcnt lgkmcnt(0)
	s_barrier
	v_cmp_ne_u32_e64 s[42:43], 1, v128
	s_cbranch_vccnz .LBB0_320
	s_setprio 1
	s_waitcnt lgkmcnt(0)
	v_mfma_f32_16x16x32_bf16 v[60:63], v[146:149], v[186:189], v[60:63]
	v_mfma_f32_16x16x32_bf16 v[56:59], v[154:157], v[186:189], v[56:59]
	v_mfma_f32_16x16x32_bf16 v[44:47], v[146:149], v[178:181], v[44:47]
	v_mfma_f32_16x16x32_bf16 v[40:43], v[154:157], v[178:181], v[40:43]
	v_mfma_f32_16x16x32_bf16 v[28:31], v[146:149], v[170:173], v[28:31]
	v_mfma_f32_16x16x32_bf16 v[24:27], v[154:157], v[170:173], v[24:27]
	v_mfma_f32_16x16x32_bf16 v[12:15], v[146:149], v[162:165], v[12:15]
	v_mfma_f32_16x16x32_bf16 v[8:11], v[154:157], v[162:165], v[8:11]
	v_mfma_f32_16x16x32_bf16 v[60:63], v[150:153], v[190:193], v[60:63]
	v_mfma_f32_16x16x32_bf16 v[56:59], v[158:161], v[190:193], v[56:59]
	v_mfma_f32_16x16x32_bf16 v[44:47], v[150:153], v[182:185], v[44:47]
	v_mfma_f32_16x16x32_bf16 v[40:43], v[158:161], v[182:185], v[40:43]
	v_mfma_f32_16x16x32_bf16 v[28:31], v[150:153], v[174:177], v[28:31]
	v_mfma_f32_16x16x32_bf16 v[24:27], v[158:161], v[174:177], v[24:27]
	v_mfma_f32_16x16x32_bf16 v[12:15], v[150:153], v[166:169], v[12:15]
	v_mfma_f32_16x16x32_bf16 v[8:11], v[158:161], v[166:169], v[8:11]
	s_setprio 0
	s_setprio 1
	v_mfma_f32_16x16x32_bf16 v[52:55], v[130:133], v[186:189], v[52:55]
	v_mfma_f32_16x16x32_bf16 v[48:51], v[138:141], v[186:189], v[48:51]
	v_mfma_f32_16x16x32_bf16 v[36:39], v[130:133], v[178:181], v[36:39]
	v_mfma_f32_16x16x32_bf16 v[32:35], v[138:141], v[178:181], v[32:35]
	v_mfma_f32_16x16x32_bf16 v[20:23], v[130:133], v[170:173], v[20:23]
	v_mfma_f32_16x16x32_bf16 v[16:19], v[138:141], v[170:173], v[16:19]
	v_mfma_f32_16x16x32_bf16 v[4:7], v[130:133], v[162:165], v[4:7]
	v_mfma_f32_16x16x32_bf16 v[0:3], v[138:141], v[162:165], v[0:3]
	v_mfma_f32_16x16x32_bf16 v[52:55], v[134:137], v[190:193], v[52:55]
	v_mfma_f32_16x16x32_bf16 v[48:51], v[142:145], v[190:193], v[48:51]
	v_mfma_f32_16x16x32_bf16 v[36:39], v[134:137], v[182:185], v[36:39]
	v_mfma_f32_16x16x32_bf16 v[32:35], v[142:145], v[182:185], v[32:35]
	v_mfma_f32_16x16x32_bf16 v[20:23], v[134:137], v[174:177], v[20:23]
	v_mfma_f32_16x16x32_bf16 v[16:19], v[142:145], v[174:177], v[16:19]
	v_mfma_f32_16x16x32_bf16 v[4:7], v[134:137], v[166:169], v[4:7]
	v_mfma_f32_16x16x32_bf16 v[0:3], v[142:145], v[166:169], v[0:3]
	s_setprio 0
.LBB0_320:
	s_add_u32 s80, s72, 0x80
	s_addc_u32 s81, s73, 0
	s_add_u32 s76, s76, 0x80
	s_addc_u32 s77, s77, 0
	s_barrier
	v_add_u32_e32 v128, 0x18000, v251
	ds_read_b128 v[146:149], v128
	ds_read_b128 v[150:153], v128 offset:1024
	ds_read_b128 v[154:157], v128 offset:2048
	ds_read_b128 v[158:161], v128 offset:3072
	v_add_u32_e32 v128, 0x1c000, v251
	ds_read_b128 v[130:133], v128
	ds_read_b128 v[134:137], v128 offset:1024
	ds_read_b128 v[138:141], v128 offset:2048
	ds_read_b128 v[142:145], v128 offset:3072
	s_add_u32 s72, s72, s9
	s_addc_u32 s73, s73, 0
	s_mov_b32 m0, s20
	s_nop 0
	global_load_lds_dwordx4 v245, s[72:73]
	s_nop 0
	s_mov_b32 m0, s21
	s_nop 0
	global_load_lds_dwordx4 v247, s[72:73]
	s_waitcnt lgkmcnt(0)
	ds_read_b128 v[162:165], v252 offset:32768
	ds_read_b128 v[166:169], v252 offset:33792
	ds_read_b128 v[170:173], v252 offset:34816
	ds_read_b128 v[174:177], v252 offset:35840
	ds_read_b128 v[178:181], v252 offset:36864
	ds_read_b128 v[182:185], v252 offset:37888
	ds_read_b128 v[186:189], v252 offset:38912
	ds_read_b128 v[190:193], v252 offset:39936
	s_waitcnt vmcnt(8)
	s_waitcnt lgkmcnt(0)
	s_barrier
	s_setprio 1
	s_waitcnt lgkmcnt(0)
	v_mfma_f32_16x16x32_bf16 v[124:127], v[146:149], v[162:165], v[124:127]
	v_mfma_f32_16x16x32_bf16 v[120:123], v[154:157], v[162:165], v[120:123]
	v_mfma_f32_16x16x32_bf16 v[108:111], v[146:149], v[170:173], v[108:111]
	v_mfma_f32_16x16x32_bf16 v[104:107], v[154:157], v[170:173], v[104:107]
	v_mfma_f32_16x16x32_bf16 v[92:95], v[146:149], v[178:181], v[92:95]
	v_mfma_f32_16x16x32_bf16 v[88:91], v[154:157], v[178:181], v[88:91]
	v_mfma_f32_16x16x32_bf16 v[76:79], v[146:149], v[186:189], v[76:79]
	v_mfma_f32_16x16x32_bf16 v[72:75], v[154:157], v[186:189], v[72:75]
	v_mfma_f32_16x16x32_bf16 v[124:127], v[150:153], v[166:169], v[124:127]
	v_mfma_f32_16x16x32_bf16 v[120:123], v[158:161], v[166:169], v[120:123]
	v_mfma_f32_16x16x32_bf16 v[108:111], v[150:153], v[174:177], v[108:111]
	v_mfma_f32_16x16x32_bf16 v[104:107], v[158:161], v[174:177], v[104:107]
	v_mfma_f32_16x16x32_bf16 v[92:95], v[150:153], v[182:185], v[92:95]
	v_mfma_f32_16x16x32_bf16 v[88:91], v[158:161], v[182:185], v[88:91]
	v_mfma_f32_16x16x32_bf16 v[76:79], v[150:153], v[190:193], v[76:79]
	v_mfma_f32_16x16x32_bf16 v[72:75], v[158:161], v[190:193], v[72:75]
	s_setprio 0
	s_setprio 1
	v_mfma_f32_16x16x32_bf16 v[116:119], v[130:133], v[162:165], v[116:119]
	v_mfma_f32_16x16x32_bf16 v[112:115], v[138:141], v[162:165], v[112:115]
	v_mfma_f32_16x16x32_bf16 v[100:103], v[130:133], v[170:173], v[100:103]
	v_mfma_f32_16x16x32_bf16 v[96:99], v[138:141], v[170:173], v[96:99]
	v_mfma_f32_16x16x32_bf16 v[84:87], v[130:133], v[178:181], v[84:87]
	v_mfma_f32_16x16x32_bf16 v[80:83], v[138:141], v[178:181], v[80:83]
	v_mfma_f32_16x16x32_bf16 v[68:71], v[130:133], v[186:189], v[68:71]
	v_mfma_f32_16x16x32_bf16 v[64:67], v[138:141], v[186:189], v[64:67]
	v_mfma_f32_16x16x32_bf16 v[116:119], v[134:137], v[166:169], v[116:119]
	v_mfma_f32_16x16x32_bf16 v[112:115], v[142:145], v[166:169], v[112:115]
	v_mfma_f32_16x16x32_bf16 v[100:103], v[134:137], v[174:177], v[100:103]
	v_mfma_f32_16x16x32_bf16 v[96:99], v[142:145], v[174:177], v[96:99]
	v_mfma_f32_16x16x32_bf16 v[84:87], v[134:137], v[182:185], v[84:87]
	v_mfma_f32_16x16x32_bf16 v[80:83], v[142:145], v[182:185], v[80:83]
	v_mfma_f32_16x16x32_bf16 v[68:71], v[134:137], v[190:193], v[68:71]
	v_mfma_f32_16x16x32_bf16 v[64:67], v[142:145], v[190:193], v[64:67]
	s_setprio 0
	s_barrier
	s_mov_b32 m0, s23
	s_nop 0
	global_load_lds_dwordx4 v246, s[76:77]
	s_nop 0
	s_mov_b32 m0, s30
	s_nop 0
	global_load_lds_dwordx4 v248, s[76:77]
	s_add_u32 s72, s74, 0x80
	s_addc_u32 s73, s75, 0
	s_mov_b32 m0, s52
	s_nop 0
	global_load_lds_dwordx4 v246, s[72:73]
	s_and_b64 vcc, exec, s[42:43]
	s_mov_b32 m0, s53
	s_nop 0
	global_load_lds_dwordx4 v248, s[72:73]
	s_mov_b32 m0, s47
	s_nop 0
	global_load_lds_dwordx4 v245, s[80:81]
	s_nop 0
	s_mov_b32 m0, s50
	s_nop 0
	global_load_lds_dwordx4 v247, s[80:81]
	ds_read_b128 v[186:189], v252 offset:49152
	ds_read_b128 v[190:193], v252 offset:50176
	ds_read_b128 v[178:181], v252 offset:51200
	ds_read_b128 v[182:185], v252 offset:52224
	ds_read_b128 v[170:173], v252 offset:53248
	ds_read_b128 v[174:177], v252 offset:54272
	ds_read_b128 v[162:165], v252 offset:55296
	ds_read_b128 v[166:169], v252 offset:56320
	s_waitcnt vmcnt(8)
	s_waitcnt lgkmcnt(0)
	s_barrier
	s_cbranch_vccnz .LBB0_317
	s_setprio 1
	s_waitcnt lgkmcnt(0)
	v_mfma_f32_16x16x32_bf16 v[60:63], v[146:149], v[186:189], v[60:63]
	v_mfma_f32_16x16x32_bf16 v[56:59], v[154:157], v[186:189], v[56:59]
	v_mfma_f32_16x16x32_bf16 v[44:47], v[146:149], v[178:181], v[44:47]
	v_mfma_f32_16x16x32_bf16 v[40:43], v[154:157], v[178:181], v[40:43]
	v_mfma_f32_16x16x32_bf16 v[28:31], v[146:149], v[170:173], v[28:31]
	v_mfma_f32_16x16x32_bf16 v[24:27], v[154:157], v[170:173], v[24:27]
	v_mfma_f32_16x16x32_bf16 v[12:15], v[146:149], v[162:165], v[12:15]
	v_mfma_f32_16x16x32_bf16 v[8:11], v[154:157], v[162:165], v[8:11]
	v_mfma_f32_16x16x32_bf16 v[60:63], v[150:153], v[190:193], v[60:63]
	v_mfma_f32_16x16x32_bf16 v[56:59], v[158:161], v[190:193], v[56:59]
	v_mfma_f32_16x16x32_bf16 v[44:47], v[150:153], v[182:185], v[44:47]
	v_mfma_f32_16x16x32_bf16 v[40:43], v[158:161], v[182:185], v[40:43]
	v_mfma_f32_16x16x32_bf16 v[28:31], v[150:153], v[174:177], v[28:31]
	v_mfma_f32_16x16x32_bf16 v[24:27], v[158:161], v[174:177], v[24:27]
	v_mfma_f32_16x16x32_bf16 v[12:15], v[150:153], v[166:169], v[12:15]
	v_mfma_f32_16x16x32_bf16 v[8:11], v[158:161], v[166:169], v[8:11]
	s_setprio 0
	s_setprio 1
	v_mfma_f32_16x16x32_bf16 v[52:55], v[130:133], v[186:189], v[52:55]
	v_mfma_f32_16x16x32_bf16 v[48:51], v[138:141], v[186:189], v[48:51]
	v_mfma_f32_16x16x32_bf16 v[36:39], v[130:133], v[178:181], v[36:39]
	v_mfma_f32_16x16x32_bf16 v[32:35], v[138:141], v[178:181], v[32:35]
	v_mfma_f32_16x16x32_bf16 v[20:23], v[130:133], v[170:173], v[20:23]
	v_mfma_f32_16x16x32_bf16 v[16:19], v[138:141], v[170:173], v[16:19]
	v_mfma_f32_16x16x32_bf16 v[4:7], v[130:133], v[162:165], v[4:7]
	v_mfma_f32_16x16x32_bf16 v[0:3], v[138:141], v[162:165], v[0:3]
	v_mfma_f32_16x16x32_bf16 v[52:55], v[134:137], v[190:193], v[52:55]
	v_mfma_f32_16x16x32_bf16 v[48:51], v[142:145], v[190:193], v[48:51]
	v_mfma_f32_16x16x32_bf16 v[36:39], v[134:137], v[182:185], v[36:39]
	v_mfma_f32_16x16x32_bf16 v[32:35], v[142:145], v[182:185], v[32:35]
	v_mfma_f32_16x16x32_bf16 v[20:23], v[134:137], v[174:177], v[20:23]
	v_mfma_f32_16x16x32_bf16 v[16:19], v[142:145], v[174:177], v[16:19]
	v_mfma_f32_16x16x32_bf16 v[4:7], v[134:137], v[166:169], v[4:7]
	v_mfma_f32_16x16x32_bf16 v[0:3], v[142:145], v[166:169], v[0:3]
	s_setprio 0
	s_branch .LBB0_317

.LBB0_413:
	v_add_u32_e32 v128, 0x10000, v208
	ds_read_b128 v[146:149], v128
	ds_read_b128 v[150:153], v128 offset:1024
	ds_read_b128 v[154:157], v128 offset:2048
	ds_read_b128 v[158:161], v128 offset:3072
	v_add_u32_e32 v128, 0x14000, v208
	ds_read_b128 v[130:133], v128
	ds_read_b128 v[134:137], v128 offset:1024
	ds_read_b128 v[138:141], v128 offset:2048
	ds_read_b128 v[142:145], v128 offset:3072
	s_mov_b32 m0, s30
	s_nop 0
	global_load_lds_dwordx4 v195, s[46:47]
	s_nop 0
	s_mov_b32 m0, s14
	s_nop 0
	global_load_lds_dwordx4 v197, s[46:47]
	s_add_u32 s38, s46, 0xfffc0080
	s_addc_u32 s39, s47, -1
	s_cmp_eq_u32 s19, 12
	s_cselect_b32 s75, s27, s39
	s_cselect_b32 s74, s99, s38
	s_cselect_b32 s63, s23, s18
	s_cselect_b32 s62, s3, s8
	s_waitcnt lgkmcnt(0)
	ds_read_b128 v[162:165], v209
	ds_read_b128 v[166:169], v209 offset:1024
	ds_read_b128 v[170:173], v209 offset:2048
	ds_read_b128 v[174:177], v209 offset:3072
	ds_read_b128 v[178:181], v209 offset:4096
	ds_read_b128 v[182:185], v209 offset:5120
	ds_read_b128 v[186:189], v209 offset:6144
	ds_read_b128 v[190:193], v209 offset:7168
	s_waitcnt vmcnt(8)
	s_waitcnt lgkmcnt(0)
	s_barrier
	s_setprio 1
	s_waitcnt lgkmcnt(0)
	v_mfma_f32_16x16x32_bf16 v[124:127], v[146:149], v[162:165], v[124:127]
	v_mfma_f32_16x16x32_bf16 v[120:123], v[154:157], v[162:165], v[120:123]
	v_mfma_f32_16x16x32_bf16 v[108:111], v[146:149], v[170:173], v[108:111]
	v_mfma_f32_16x16x32_bf16 v[104:107], v[154:157], v[170:173], v[104:107]
	v_mfma_f32_16x16x32_bf16 v[92:95], v[146:149], v[178:181], v[92:95]
	v_mfma_f32_16x16x32_bf16 v[88:91], v[154:157], v[178:181], v[88:91]
	v_mfma_f32_16x16x32_bf16 v[76:79], v[146:149], v[186:189], v[76:79]
	v_mfma_f32_16x16x32_bf16 v[72:75], v[154:157], v[186:189], v[72:75]
	v_mfma_f32_16x16x32_bf16 v[124:127], v[150:153], v[166:169], v[124:127]
	v_mfma_f32_16x16x32_bf16 v[120:123], v[158:161], v[166:169], v[120:123]
	v_mfma_f32_16x16x32_bf16 v[108:111], v[150:153], v[174:177], v[108:111]
	v_mfma_f32_16x16x32_bf16 v[104:107], v[158:161], v[174:177], v[104:107]
	v_mfma_f32_16x16x32_bf16 v[92:95], v[150:153], v[182:185], v[92:95]
	v_mfma_f32_16x16x32_bf16 v[88:91], v[158:161], v[182:185], v[88:91]
	v_mfma_f32_16x16x32_bf16 v[76:79], v[150:153], v[190:193], v[76:79]
	v_mfma_f32_16x16x32_bf16 v[72:75], v[158:161], v[190:193], v[72:75]
	s_setprio 0
	s_setprio 1
	v_mfma_f32_16x16x32_bf16 v[116:119], v[130:133], v[162:165], v[116:119]
	v_mfma_f32_16x16x32_bf16 v[112:115], v[138:141], v[162:165], v[112:115]
	v_mfma_f32_16x16x32_bf16 v[100:103], v[130:133], v[170:173], v[100:103]
	v_mfma_f32_16x16x32_bf16 v[96:99], v[138:141], v[170:173], v[96:99]
	v_mfma_f32_16x16x32_bf16 v[84:87], v[130:133], v[178:181], v[84:87]
	v_mfma_f32_16x16x32_bf16 v[80:83], v[138:141], v[178:181], v[80:83]
	v_mfma_f32_16x16x32_bf16 v[68:71], v[130:133], v[186:189], v[68:71]
	v_mfma_f32_16x16x32_bf16 v[64:67], v[138:141], v[186:189], v[64:67]
	v_mfma_f32_16x16x32_bf16 v[116:119], v[134:137], v[166:169], v[116:119]
	v_mfma_f32_16x16x32_bf16 v[112:115], v[142:145], v[166:169], v[112:115]
	v_mfma_f32_16x16x32_bf16 v[100:103], v[134:137], v[174:177], v[100:103]
	v_mfma_f32_16x16x32_bf16 v[96:99], v[142:145], v[174:177], v[96:99]
	v_mfma_f32_16x16x32_bf16 v[84:87], v[134:137], v[182:185], v[84:87]
	v_mfma_f32_16x16x32_bf16 v[80:83], v[142:145], v[182:185], v[80:83]
	v_mfma_f32_16x16x32_bf16 v[68:71], v[134:137], v[190:193], v[68:71]
	v_mfma_f32_16x16x32_bf16 v[64:67], v[142:145], v[190:193], v[64:67]
	s_setprio 0
	s_barrier
	s_mov_b32 m0, s67
	s_nop 0
	global_load_lds_dwordx4 v196, s[62:63]
	s_add_u32 s44, s62, 0x40000
	s_mov_b32 m0, s86
	s_nop 0
	global_load_lds_dwordx4 v198, s[62:63]
	s_addc_u32 s45, s63, 0
	s_mov_b32 m0, s87
	s_nop 0
	global_load_lds_dwordx4 v196, s[44:45]
	v_cndmask_b32_e64 v128, 0, 1, s[72:73]
	s_mov_b32 m0, s88
	s_nop 0
	global_load_lds_dwordx4 v198, s[44:45]
	v_cmp_ne_u32_e64 s[44:45], 1, v128
	s_mov_b32 m0, s51
	s_nop 0
	global_load_lds_dwordx4 v195, s[74:75]
	s_andn2_b64 vcc, exec, s[72:73]
	s_mov_b32 m0, s89
	s_nop 0
	global_load_lds_dwordx4 v197, s[74:75]
	ds_read_b128 v[186:189], v209 offset:16384
	ds_read_b128 v[190:193], v209 offset:17408
	ds_read_b128 v[178:181], v209 offset:18432
	ds_read_b128 v[182:185], v209 offset:19456
	ds_read_b128 v[170:173], v209 offset:20480
	ds_read_b128 v[174:177], v209 offset:21504
	ds_read_b128 v[162:165], v209 offset:22528
	ds_read_b128 v[166:169], v209 offset:23552
	s_waitcnt vmcnt(8)
	s_waitcnt lgkmcnt(0)
	s_barrier
	s_cbranch_vccnz .LBB0_415
	s_setprio 1
	s_waitcnt lgkmcnt(0)
	v_mfma_f32_16x16x32_bf16 v[60:63], v[146:149], v[186:189], v[60:63]
	v_mfma_f32_16x16x32_bf16 v[56:59], v[154:157], v[186:189], v[56:59]
	v_mfma_f32_16x16x32_bf16 v[44:47], v[146:149], v[178:181], v[44:47]
	v_mfma_f32_16x16x32_bf16 v[40:43], v[154:157], v[178:181], v[40:43]
	v_mfma_f32_16x16x32_bf16 v[28:31], v[146:149], v[170:173], v[28:31]
	v_mfma_f32_16x16x32_bf16 v[24:27], v[154:157], v[170:173], v[24:27]
	v_mfma_f32_16x16x32_bf16 v[12:15], v[146:149], v[162:165], v[12:15]
	v_mfma_f32_16x16x32_bf16 v[8:11], v[154:157], v[162:165], v[8:11]
	v_mfma_f32_16x16x32_bf16 v[60:63], v[150:153], v[190:193], v[60:63]
	v_mfma_f32_16x16x32_bf16 v[56:59], v[158:161], v[190:193], v[56:59]
	v_mfma_f32_16x16x32_bf16 v[44:47], v[150:153], v[182:185], v[44:47]
	v_mfma_f32_16x16x32_bf16 v[40:43], v[158:161], v[182:185], v[40:43]
	v_mfma_f32_16x16x32_bf16 v[28:31], v[150:153], v[174:177], v[28:31]
	v_mfma_f32_16x16x32_bf16 v[24:27], v[158:161], v[174:177], v[24:27]
	v_mfma_f32_16x16x32_bf16 v[12:15], v[150:153], v[166:169], v[12:15]
	v_mfma_f32_16x16x32_bf16 v[8:11], v[158:161], v[166:169], v[8:11]
	s_setprio 0
	s_setprio 1
	v_mfma_f32_16x16x32_bf16 v[52:55], v[130:133], v[186:189], v[52:55]
	v_mfma_f32_16x16x32_bf16 v[48:51], v[138:141], v[186:189], v[48:51]
	v_mfma_f32_16x16x32_bf16 v[36:39], v[130:133], v[178:181], v[36:39]
	v_mfma_f32_16x16x32_bf16 v[32:35], v[138:141], v[178:181], v[32:35]
	v_mfma_f32_16x16x32_bf16 v[20:23], v[130:133], v[170:173], v[20:23]
	v_mfma_f32_16x16x32_bf16 v[16:19], v[138:141], v[170:173], v[16:19]
	v_mfma_f32_16x16x32_bf16 v[4:7], v[130:133], v[162:165], v[4:7]
	v_mfma_f32_16x16x32_bf16 v[0:3], v[138:141], v[162:165], v[0:3]
	v_mfma_f32_16x16x32_bf16 v[52:55], v[134:137], v[190:193], v[52:55]
	v_mfma_f32_16x16x32_bf16 v[48:51], v[142:145], v[190:193], v[48:51]
	v_mfma_f32_16x16x32_bf16 v[36:39], v[134:137], v[182:185], v[36:39]
	v_mfma_f32_16x16x32_bf16 v[32:35], v[142:145], v[182:185], v[32:35]
	v_mfma_f32_16x16x32_bf16 v[20:23], v[134:137], v[174:177], v[20:23]
	v_mfma_f32_16x16x32_bf16 v[16:19], v[142:145], v[174:177], v[16:19]
	v_mfma_f32_16x16x32_bf16 v[4:7], v[134:137], v[166:169], v[4:7]
	v_mfma_f32_16x16x32_bf16 v[0:3], v[142:145], v[166:169], v[0:3]
	s_setprio 0
.LBB0_415:
	s_add_u32 s76, s74, 0x80
	s_addc_u32 s77, s75, 0
	s_add_u32 s38, s62, 0x80
	s_addc_u32 s39, s63, 0
	s_barrier
	v_add_u32_e32 v128, 0x18000, v208
	ds_read_b128 v[146:149], v128
	ds_read_b128 v[150:153], v128 offset:1024
	ds_read_b128 v[154:157], v128 offset:2048
	ds_read_b128 v[158:161], v128 offset:3072
	v_add_u32_e32 v128, 0x1c000, v208
	ds_read_b128 v[130:133], v128
	ds_read_b128 v[134:137], v128 offset:1024
	ds_read_b128 v[138:141], v128 offset:2048
	ds_read_b128 v[142:145], v128 offset:3072
	s_add_u32 s74, s74, 0x40000
	s_addc_u32 s75, s75, 0
	s_mov_b32 m0, s92
	s_nop 0
	global_load_lds_dwordx4 v195, s[74:75]
	s_nop 0
	s_mov_b32 m0, s93
	s_nop 0
	global_load_lds_dwordx4 v197, s[74:75]
	s_waitcnt lgkmcnt(0)
	ds_read_b128 v[162:165], v209 offset:32768
	ds_read_b128 v[166:169], v209 offset:33792
	ds_read_b128 v[170:173], v209 offset:34816
	ds_read_b128 v[174:177], v209 offset:35840
	ds_read_b128 v[178:181], v209 offset:36864
	ds_read_b128 v[182:185], v209 offset:37888
	ds_read_b128 v[186:189], v209 offset:38912
	ds_read_b128 v[190:193], v209 offset:39936
	s_waitcnt vmcnt(8)
	s_waitcnt lgkmcnt(0)
	s_barrier
	s_setprio 1
	s_waitcnt lgkmcnt(0)
	v_mfma_f32_16x16x32_bf16 v[124:127], v[146:149], v[162:165], v[124:127]
	v_mfma_f32_16x16x32_bf16 v[120:123], v[154:157], v[162:165], v[120:123]
	v_mfma_f32_16x16x32_bf16 v[108:111], v[146:149], v[170:173], v[108:111]
	v_mfma_f32_16x16x32_bf16 v[104:107], v[154:157], v[170:173], v[104:107]
	v_mfma_f32_16x16x32_bf16 v[92:95], v[146:149], v[178:181], v[92:95]
	v_mfma_f32_16x16x32_bf16 v[88:91], v[154:157], v[178:181], v[88:91]
	v_mfma_f32_16x16x32_bf16 v[76:79], v[146:149], v[186:189], v[76:79]
	v_mfma_f32_16x16x32_bf16 v[72:75], v[154:157], v[186:189], v[72:75]
	v_mfma_f32_16x16x32_bf16 v[124:127], v[150:153], v[166:169], v[124:127]
	v_mfma_f32_16x16x32_bf16 v[120:123], v[158:161], v[166:169], v[120:123]
	v_mfma_f32_16x16x32_bf16 v[108:111], v[150:153], v[174:177], v[108:111]
	v_mfma_f32_16x16x32_bf16 v[104:107], v[158:161], v[174:177], v[104:107]
	v_mfma_f32_16x16x32_bf16 v[92:95], v[150:153], v[182:185], v[92:95]
	v_mfma_f32_16x16x32_bf16 v[88:91], v[158:161], v[182:185], v[88:91]
	v_mfma_f32_16x16x32_bf16 v[76:79], v[150:153], v[190:193], v[76:79]
	v_mfma_f32_16x16x32_bf16 v[72:75], v[158:161], v[190:193], v[72:75]
	s_setprio 0
	s_setprio 1
	v_mfma_f32_16x16x32_bf16 v[116:119], v[130:133], v[162:165], v[116:119]
	v_mfma_f32_16x16x32_bf16 v[112:115], v[138:141], v[162:165], v[112:115]
	v_mfma_f32_16x16x32_bf16 v[100:103], v[130:133], v[170:173], v[100:103]
	v_mfma_f32_16x16x32_bf16 v[96:99], v[138:141], v[170:173], v[96:99]
	v_mfma_f32_16x16x32_bf16 v[84:87], v[130:133], v[178:181], v[84:87]
	v_mfma_f32_16x16x32_bf16 v[80:83], v[138:141], v[178:181], v[80:83]
	v_mfma_f32_16x16x32_bf16 v[68:71], v[130:133], v[186:189], v[68:71]
	v_mfma_f32_16x16x32_bf16 v[64:67], v[138:141], v[186:189], v[64:67]
	v_mfma_f32_16x16x32_bf16 v[116:119], v[134:137], v[166:169], v[116:119]
	v_mfma_f32_16x16x32_bf16 v[112:115], v[142:145], v[166:169], v[112:115]
	v_mfma_f32_16x16x32_bf16 v[100:103], v[134:137], v[174:177], v[100:103]
	v_mfma_f32_16x16x32_bf16 v[96:99], v[142:145], v[174:177], v[96:99]
	v_mfma_f32_16x16x32_bf16 v[84:87], v[134:137], v[182:185], v[84:87]
	v_mfma_f32_16x16x32_bf16 v[80:83], v[142:145], v[182:185], v[80:83]
	v_mfma_f32_16x16x32_bf16 v[68:71], v[134:137], v[190:193], v[68:71]
	v_mfma_f32_16x16x32_bf16 v[64:67], v[142:145], v[190:193], v[64:67]
	s_setprio 0
	s_barrier
	s_mov_b32 m0, s95
	s_nop 0
	global_load_lds_dwordx4 v196, s[38:39]
	s_nop 0
	s_mov_b32 m0, s96
	s_nop 0
	global_load_lds_dwordx4 v198, s[38:39]
	s_add_u32 s38, s62, 0x40080
	s_addc_u32 s39, s63, 0
	s_mov_b32 m0, s65
	s_nop 0
	global_load_lds_dwordx4 v196, s[38:39]
	s_and_b64 vcc, exec, s[44:45]
	s_mov_b32 m0, s50
	s_nop 0
	global_load_lds_dwordx4 v198, s[38:39]
	s_mov_b32 m0, s97
	s_nop 0
	global_load_lds_dwordx4 v195, s[76:77]
	s_nop 0
	s_mov_b32 m0, s9
	s_nop 0
	global_load_lds_dwordx4 v197, s[76:77]
	ds_read_b128 v[186:189], v209 offset:49152
	ds_read_b128 v[190:193], v209 offset:50176
	ds_read_b128 v[178:181], v209 offset:51200
	ds_read_b128 v[182:185], v209 offset:52224
	ds_read_b128 v[170:173], v209 offset:53248
	ds_read_b128 v[174:177], v209 offset:54272
	ds_read_b128 v[162:165], v209 offset:55296
	ds_read_b128 v[166:169], v209 offset:56320
	s_waitcnt vmcnt(8)
	s_waitcnt lgkmcnt(0)
	s_barrier
	s_cbranch_vccnz .LBB0_412
	s_setprio 1
	s_waitcnt lgkmcnt(0)
	v_mfma_f32_16x16x32_bf16 v[60:63], v[146:149], v[186:189], v[60:63]
	v_mfma_f32_16x16x32_bf16 v[56:59], v[154:157], v[186:189], v[56:59]
	v_mfma_f32_16x16x32_bf16 v[44:47], v[146:149], v[178:181], v[44:47]
	v_mfma_f32_16x16x32_bf16 v[40:43], v[154:157], v[178:181], v[40:43]
	v_mfma_f32_16x16x32_bf16 v[28:31], v[146:149], v[170:173], v[28:31]
	v_mfma_f32_16x16x32_bf16 v[24:27], v[154:157], v[170:173], v[24:27]
	v_mfma_f32_16x16x32_bf16 v[12:15], v[146:149], v[162:165], v[12:15]
	v_mfma_f32_16x16x32_bf16 v[8:11], v[154:157], v[162:165], v[8:11]
	v_mfma_f32_16x16x32_bf16 v[60:63], v[150:153], v[190:193], v[60:63]
	v_mfma_f32_16x16x32_bf16 v[56:59], v[158:161], v[190:193], v[56:59]
	v_mfma_f32_16x16x32_bf16 v[44:47], v[150:153], v[182:185], v[44:47]
	v_mfma_f32_16x16x32_bf16 v[40:43], v[158:161], v[182:185], v[40:43]
	v_mfma_f32_16x16x32_bf16 v[28:31], v[150:153], v[174:177], v[28:31]
	v_mfma_f32_16x16x32_bf16 v[24:27], v[158:161], v[174:177], v[24:27]
	v_mfma_f32_16x16x32_bf16 v[12:15], v[150:153], v[166:169], v[12:15]
	v_mfma_f32_16x16x32_bf16 v[8:11], v[158:161], v[166:169], v[8:11]
	s_setprio 0
	s_setprio 1
	v_mfma_f32_16x16x32_bf16 v[52:55], v[130:133], v[186:189], v[52:55]
	v_mfma_f32_16x16x32_bf16 v[48:51], v[138:141], v[186:189], v[48:51]
	v_mfma_f32_16x16x32_bf16 v[36:39], v[130:133], v[178:181], v[36:39]
	v_mfma_f32_16x16x32_bf16 v[32:35], v[138:141], v[178:181], v[32:35]
	v_mfma_f32_16x16x32_bf16 v[20:23], v[130:133], v[170:173], v[20:23]
	v_mfma_f32_16x16x32_bf16 v[16:19], v[138:141], v[170:173], v[16:19]
	v_mfma_f32_16x16x32_bf16 v[4:7], v[130:133], v[162:165], v[4:7]
	v_mfma_f32_16x16x32_bf16 v[0:3], v[138:141], v[162:165], v[0:3]
	v_mfma_f32_16x16x32_bf16 v[52:55], v[134:137], v[190:193], v[52:55]
	v_mfma_f32_16x16x32_bf16 v[48:51], v[142:145], v[190:193], v[48:51]
	v_mfma_f32_16x16x32_bf16 v[36:39], v[134:137], v[182:185], v[36:39]
	v_mfma_f32_16x16x32_bf16 v[32:35], v[142:145], v[182:185], v[32:35]
	v_mfma_f32_16x16x32_bf16 v[20:23], v[134:137], v[174:177], v[20:23]
	v_mfma_f32_16x16x32_bf16 v[16:19], v[142:145], v[174:177], v[16:19]
	v_mfma_f32_16x16x32_bf16 v[4:7], v[134:137], v[166:169], v[4:7]
	v_mfma_f32_16x16x32_bf16 v[0:3], v[142:145], v[166:169], v[0:3]
	s_setprio 0
	s_branch .LBB0_412
